# v33 + hgrn state-update ka/d LDS fragments fetched behind the O3 MFMAs that last read their registers
# speedup vs baseline: 1.0033x; 1.0033x over previous
.LBB0_525:
	s_min_u32 s54, s91, 28
	s_lshl_b32 s92, s91, 6
	s_lshl_b32 s54, s54, 6
	s_or_b32 s66, s92, 64
	s_add_i32 s58, s54, 0xc0
	s_add_u32 s54, s62, s58
	s_addc_u32 s55, s63, 0
	v_add_u32_e32 v32, v175, v162
	s_add_u32 s58, s60, s58
	ds_write_b128 v32, v[16:19]
	v_add_u32_e32 v16, v175, v163
	s_addc_u32 s59, 0, 0
	ds_write_b128 v16, v[20:23]
	v_lshl_add_u64 v[16:17], v[88:89], 0, s[66:67]
	s_add_u32 s72, s54, s86
	v_lshlrev_b64 v[16:17], 8, v[16:17]
	s_addc_u32 s73, s55, 0
	v_lshl_add_u64 v[16:17], v[90:91], 0, v[16:17]
	s_lshl_b64 s[72:73], s[72:73], 8
	global_load_dwordx2 v[100:101], v[16:17], off
	global_load_dwordx2 v[98:99], v[16:17], off offset:32
	global_load_dwordx2 v[96:97], v[16:17], off offset:64
	global_load_dwordx2 v[94:95], v[16:17], off offset:96
	v_lshl_add_u64 v[16:17], v[70:71], 0, s[72:73]
	s_lshl_b64 s[58:59], s[58:59], 11
	global_load_dword v194, v[16:17], off
	v_lshl_add_u64 v[16:17], v[72:73], 0, s[58:59]
	s_or_b32 s58, s72, 0x100
	s_mov_b32 s59, s73
	v_lshl_add_u64 v[18:19], v[70:71], 0, s[58:59]
	s_or_b32 s58, s72, 0x200
	global_load_dword v200, v[16:17], off
	global_load_dword v186, v[18:19], off
	global_load_dword v198, v[16:17], off offset:2048
	v_lshl_add_u64 v[18:19], v[70:71], 0, s[58:59]
	global_load_dword v181, v[18:19], off
	v_add_co_u32_e32 v18, vcc, s61, v16
	s_or_b32 s58, s72, 0x300
	s_nop 0
	v_addc_co_u32_e32 v19, vcc, 0, v17, vcc
	v_add_co_u32_e32 v20, vcc, s87, v16
	v_lshl_add_u64 v[22:23], v[70:71], 0, s[58:59]
	s_nop 0
	v_addc_co_u32_e32 v21, vcc, 0, v17, vcc
	s_or_b32 s58, s72, 0x400
	global_load_dword v201, v[20:21], off offset:-4096
	global_load_dword v179, v[22:23], off
	global_load_dword v185, v[18:19], off offset:2048
	v_lshl_add_u64 v[18:19], v[70:71], 0, s[58:59]
	s_or_b32 s58, s72, 0x500
	global_load_dword v177, v[18:19], off
	global_load_dword v196, v[20:21], off
	v_lshl_add_u64 v[18:19], v[70:71], 0, s[58:59]
	s_or_b32 s58, s72, 0x600
	v_add_co_u32_e32 v16, vcc, s88, v16
	global_load_dword v173, v[18:19], off
	global_load_dword v187, v[20:21], off offset:2048
	v_lshl_add_u64 v[18:19], v[70:71], 0, s[58:59]
	v_addc_co_u32_e32 v17, vcc, 0, v17, vcc
	s_or_b32 s72, s72, 0x700
	global_load_dword v166, v[18:19], off
	global_load_dword v167, v[16:17], off
	v_lshl_add_u64 v[18:19], v[70:71], 0, s[72:73]
	global_load_dword v164, v[18:19], off
	global_load_dword v165, v[16:17], off offset:2048
	v_mov_b32_e32 v17, s55
	v_or_b32_e32 v16, s54, v93
	v_lshl_add_u64 v[20:21], s[54:55], 0, v[68:69]
	v_lshlrev_b64 v[16:17], 8, v[16:17]
	v_lshlrev_b64 v[20:21], 8, v[20:21]
	v_lshl_add_u64 v[16:17], v[74:75], 0, v[16:17]
	v_lshl_add_u64 v[20:21], v[74:75], 0, v[20:21]
	global_load_dwordx4 v[16:19], v[16:17], off
	s_nop 0
	global_load_dwordx4 v[20:23], v[20:21], off
	ds_read_b128 v[56:59], v218
	ds_read_b128 v[48:51], v218 offset:64
	ds_read_b128 v[44:47], v218 offset:128
	ds_read_b128 v[40:43], v218 offset:192
	ds_read_b128 v[36:39], v204 offset:17408
	ds_read_b128 v[228:231], v204 offset:17472
	ds_read_b128 v[232:235], v204 offset:17536
	ds_read_b128 v[236:239], v204 offset:17600
	s_waitcnt lgkmcnt(3)
	v_mfma_f32_16x16x32_bf16 v[32:35], v[36:39], v[56:59], 0
	s_waitcnt lgkmcnt(2)
	v_mfma_f32_16x16x32_bf16 v[32:35], v[228:231], v[48:51], v[32:35]
	s_waitcnt lgkmcnt(1)
	v_mfma_f32_16x16x32_bf16 v[32:35], v[232:235], v[44:47], v[32:35]
	s_waitcnt lgkmcnt(0)
	v_mfma_f32_16x16x32_bf16 v[32:35], v[236:239], v[40:43], v[32:35]
	ds_read_b128 v[36:39], v204 offset:21760
	ds_read_b128 v[228:231], v204 offset:21824
	ds_read_b128 v[232:235], v204 offset:21888
	ds_read_b128 v[236:239], v204 offset:21952
	s_nop 3
	v_cndmask_b32_e64 v52, 0, v32, s[18:19]
	v_cndmask_b32_e64 v53, 0, v33, s[20:21]
	v_cndmask_b32_e64 v54, 0, v34, s[22:23]
	v_cndmask_b32_e64 v55, 0, v35, s[24:25]
	v_cvt_pk_bf16_f32 v64, v52, v53
	v_cvt_pk_bf16_f32 v65, v54, v55
	s_waitcnt lgkmcnt(3)
	v_mfma_f32_16x16x32_bf16 v[32:35], v[36:39], v[56:59], 0
	s_waitcnt lgkmcnt(2)
	v_mfma_f32_16x16x32_bf16 v[32:35], v[228:231], v[48:51], v[32:35]
	s_waitcnt lgkmcnt(1)
	v_mfma_f32_16x16x32_bf16 v[32:35], v[232:235], v[44:47], v[32:35]
	s_waitcnt lgkmcnt(0)
	v_mfma_f32_16x16x32_bf16 v[32:35], v[236:239], v[40:43], v[32:35]
	ds_read_b128 v[36:39], v204 offset:26112
	ds_read_b128 v[228:231], v204 offset:26176
	ds_read_b128 v[232:235], v204 offset:26240
	ds_read_b128 v[236:239], v204 offset:26304
	s_nop 3
	v_cndmask_b32_e64 v60, 0, v32, s[26:27]
	v_cndmask_b32_e64 v61, 0, v33, s[28:29]
	v_cndmask_b32_e64 v62, 0, v34, s[30:31]
	v_cndmask_b32_e64 v63, 0, v35, s[34:35]
	v_cvt_pk_bf16_f32 v66, v60, v61
	v_cvt_pk_bf16_f32 v67, v62, v63
	s_waitcnt lgkmcnt(3)
	v_mfma_f32_16x16x32_bf16 v[32:35], v[36:39], v[56:59], 0
	s_waitcnt lgkmcnt(2)
	v_mfma_f32_16x16x32_bf16 v[32:35], v[228:231], v[48:51], v[32:35]
	s_waitcnt lgkmcnt(1)
	v_mfma_f32_16x16x32_bf16 v[32:35], v[232:235], v[44:47], v[32:35]
	s_waitcnt lgkmcnt(0)
	v_mfma_f32_16x16x32_bf16 v[32:35], v[236:239], v[40:43], v[32:35]
	ds_read_b128 v[36:39], v204 offset:30464
	ds_read_b128 v[228:231], v204 offset:30528
	ds_read_b128 v[232:235], v204 offset:30592
	ds_read_b128 v[236:239], v204 offset:30656
	s_nop 3
	v_cndmask_b32_e64 v86, 0, v32, s[36:37]
	v_cndmask_b32_e64 v149, 0, v33, s[38:39]
	v_cndmask_b32_e64 v150, 0, v34, s[40:41]
	v_cndmask_b32_e64 v151, 0, v35, s[42:43]
	v_cvt_pk_bf16_f32 v60, v86, v149
	v_cvt_pk_bf16_f32 v61, v150, v151
	v_add_u32_e32 v86, v178, v203
	s_waitcnt lgkmcnt(3)
	v_mfma_f32_16x16x32_bf16 v[32:35], v[36:39], v[56:59], 0
	s_waitcnt lgkmcnt(2)
	v_mfma_f32_16x16x32_bf16 v[32:35], v[228:231], v[48:51], v[32:35]
	s_waitcnt lgkmcnt(1)
	v_mfma_f32_16x16x32_bf16 v[32:35], v[232:235], v[44:47], v[32:35]
	s_waitcnt lgkmcnt(0)
	v_mfma_f32_16x16x32_bf16 v[32:35], v[236:239], v[40:43], v[32:35]
	ds_read_b64_tr_b16 v[150:151], v205 offset:43520
	ds_read_b64_tr_b16 v[152:153], v205 offset:47872
	ds_read_b128 v[228:231], v219
	ds_read_b128 v[232:235], v219 offset:64
	ds_read_b128 v[236:239], v219 offset:128
	ds_read_b128 v[240:243], v219 offset:192
	s_nop 1
	v_cndmask_b32_e64 v32, 0, v32, s[44:45]
	v_cndmask_b32_e64 v33, 0, v33, s[46:47]
	v_cndmask_b32_e64 v34, 0, v34, s[48:49]
	v_cndmask_b32_e64 v35, 0, v35, s[50:51]
	v_cvt_pk_bf16_f32 v62, v32, v33
	v_cvt_pk_bf16_f32 v63, v34, v35
	ds_read_b64_tr_b16 v[32:33], v205 offset:34816
	ds_read_b64_tr_b16 v[34:35], v205 offset:39168
	s_waitcnt lgkmcnt(0)
	v_mfma_f32_16x16x32_bf16 v[32:35], v[32:35], v[64:67], 0
	ds_read_b64_tr_b16 v[36:37], v206 offset:34816
	ds_read_b64_tr_b16 v[38:39], v206 offset:39168
	v_mfma_f32_16x16x32_bf16 v[32:35], v[150:153], v[60:63], v[32:35]
	ds_read_b64_tr_b16 v[150:151], v206 offset:43520
	ds_read_b64_tr_b16 v[152:153], v206 offset:47872
	v_mfma_f32_16x16x32_bf16 v[32:35], v[228:231], v[56:59], v[32:35]
	ds_read_b128 v[228:231], v220
	v_mfma_f32_16x16x32_bf16 v[32:35], v[232:235], v[48:51], v[32:35]
	ds_read_b128 v[232:235], v220 offset:64
	v_mfma_f32_16x16x32_bf16 v[32:35], v[236:239], v[44:47], v[32:35]
	ds_read_b128 v[236:239], v220 offset:128
	v_mfma_f32_16x16x32_bf16 v[32:35], v[240:243], v[40:43], v[32:35]
	ds_read_b128 v[240:243], v220 offset:192
	s_waitcnt lgkmcnt(6)
	v_mfma_f32_16x16x32_bf16 v[36:39], v[36:39], v[64:67], 0
	ds_read_b64_tr_b16 v[52:53], v207 offset:34816
	ds_read_b64_tr_b16 v[54:55], v207 offset:39168
	s_waitcnt lgkmcnt(6)
	v_mfma_f32_16x16x32_bf16 v[36:39], v[150:153], v[60:63], v[36:39]
	ds_read_b64_tr_b16 v[150:151], v207 offset:43520
	ds_read_b64_tr_b16 v[152:153], v207 offset:47872
	s_waitcnt lgkmcnt(7)
	v_mfma_f32_16x16x32_bf16 v[36:39], v[228:231], v[56:59], v[36:39]
	ds_read_b128 v[228:231], v221
	s_waitcnt lgkmcnt(7)
	v_mfma_f32_16x16x32_bf16 v[36:39], v[232:235], v[48:51], v[36:39]
	ds_read_b128 v[232:235], v221 offset:64
	s_waitcnt lgkmcnt(7)
	v_mfma_f32_16x16x32_bf16 v[36:39], v[236:239], v[44:47], v[36:39]
	ds_read_b128 v[236:239], v221 offset:128
	s_waitcnt lgkmcnt(7)
	v_mfma_f32_16x16x32_bf16 v[36:39], v[240:243], v[40:43], v[36:39]
	ds_read_b128 v[240:243], v221 offset:192
	s_waitcnt lgkmcnt(6)
	v_mfma_f32_16x16x32_bf16 v[52:55], v[52:55], v[64:67], 0
	ds_read_b64_tr_b16 v[244:245], v208 offset:34816
	ds_read_b64_tr_b16 v[246:247], v208 offset:39168
	s_waitcnt lgkmcnt(6)
	v_mfma_f32_16x16x32_bf16 v[52:55], v[150:153], v[60:63], v[52:55]
	ds_read_b64_tr_b16 v[150:151], v208 offset:43520
	ds_read_b64_tr_b16 v[152:153], v208 offset:47872
	s_waitcnt lgkmcnt(7)
	v_mfma_f32_16x16x32_bf16 v[52:55], v[228:231], v[56:59], v[52:55]
	ds_read_b128 v[228:231], v222
	s_waitcnt lgkmcnt(7)
	v_mfma_f32_16x16x32_bf16 v[52:55], v[232:235], v[48:51], v[52:55]
	ds_read_b128 v[232:235], v222 offset:64
	s_waitcnt lgkmcnt(7)
	v_mfma_f32_16x16x32_bf16 v[52:55], v[236:239], v[44:47], v[52:55]
	ds_read_b128 v[236:239], v222 offset:128
	s_waitcnt lgkmcnt(7)
	v_mfma_f32_16x16x32_bf16 v[52:55], v[240:243], v[40:43], v[52:55]
	ds_read_b128 v[240:243], v222 offset:192
	s_waitcnt lgkmcnt(6)
	v_mfma_f32_16x16x32_bf16 v[64:67], v[244:247], v[64:67], 0
	s_waitcnt lgkmcnt(4)
	v_mfma_f32_16x16x32_bf16 v[64:67], v[150:153], v[60:63], v[64:67]
	ds_read_b64_tr_b16 v[60:61], v209 offset:17408
	ds_read_b64_tr_b16 v[62:63], v209 offset:18496
	s_waitcnt lgkmcnt(5)
	v_mfma_f32_16x16x32_bf16 v[64:67], v[228:231], v[56:59], v[64:67]
	ds_read_b128 v[56:59], v182
	s_waitcnt lgkmcnt(5)
	v_mfma_f32_16x16x32_bf16 v[64:67], v[232:235], v[48:51], v[64:67]
	ds_read_b64_tr_b16 v[48:49], v209 offset:26112
	ds_read_b64_tr_b16 v[50:51], v209 offset:27200
	s_waitcnt lgkmcnt(6)
	v_mfma_f32_16x16x32_bf16 v[64:67], v[236:239], v[44:47], v[64:67]
	ds_read_b128 v[44:47], v180
	s_waitcnt lgkmcnt(6)
	v_mfma_f32_16x16x32_bf16 v[40:43], v[240:243], v[40:43], v[64:67]
	ds_read_b64_tr_b16 v[244:245], v86 offset:34816
	ds_read_b64_tr_b16 v[246:247], v86 offset:35904
	ds_read_b64_tr_b16 v[228:229], v86 offset:34848
	ds_read_b64_tr_b16 v[230:231], v86 offset:35936
	ds_read_b64_tr_b16 v[150:151], v86 offset:43520
	ds_read_b64_tr_b16 v[152:153], v86 offset:44608
	ds_read_b64_tr_b16 v[240:241], v86 offset:43552
	ds_read_b64_tr_b16 v[242:243], v86 offset:44640
	s_waitcnt lgkmcnt(6)
	v_mfma_f32_16x16x32_bf16 v[64:67], v[60:63], v[244:247], 0
	s_waitcnt lgkmcnt(4)
	v_mfma_f32_16x16x32_bf16 v[236:239], v[60:63], v[228:231], 0
	s_waitcnt lgkmcnt(2)
	v_mfma_f32_16x16x32_bf16 v[64:67], v[48:51], v[150:153], v[64:67]
	s_waitcnt lgkmcnt(0)
	v_mfma_f32_16x16x32_bf16 v[236:239], v[48:51], v[240:243], v[236:239]
	ds_read_b64_tr_b16 v[244:245], v86 offset:34880
	ds_read_b64_tr_b16 v[246:247], v86 offset:35968
	ds_read_b64_tr_b16 v[228:229], v86 offset:34912
	ds_read_b64_tr_b16 v[230:231], v86 offset:36000
	ds_read_b64_tr_b16 v[150:151], v86 offset:43584
	ds_read_b64_tr_b16 v[152:153], v86 offset:44672
	ds_read_b64_tr_b16 v[240:241], v86 offset:43616
	ds_read_b64_tr_b16 v[242:243], v86 offset:44704
	s_nop 3
	v_pk_mul_f32 v[66:67], v[58:59], v[66:67]
	v_pk_mul_f32 v[64:65], v[56:57], v[64:65]
	v_pk_fma_f32 v[104:105], v[104:105], v[46:47], v[66:67]
	v_pk_fma_f32 v[102:103], v[102:103], v[44:45], v[64:65]
	v_pk_mul_f32 v[238:239], v[58:59], v[238:239]
	v_pk_mul_f32 v[236:237], v[56:57], v[236:237]
	v_pk_fma_f32 v[114:115], v[114:115], v[46:47], v[238:239]
	v_pk_fma_f32 v[108:109], v[108:109], v[44:45], v[236:237]
	s_waitcnt lgkmcnt(6)
	v_mfma_f32_16x16x32_bf16 v[64:67], v[60:63], v[244:247], 0
	s_waitcnt lgkmcnt(4)
	v_mfma_f32_16x16x32_bf16 v[236:239], v[60:63], v[228:231], 0
	s_waitcnt lgkmcnt(2)
	v_mfma_f32_16x16x32_bf16 v[64:67], v[48:51], v[150:153], v[64:67]
	s_waitcnt lgkmcnt(0)
	v_mfma_f32_16x16x32_bf16 v[236:239], v[48:51], v[240:243], v[236:239]
	ds_read_b64_tr_b16 v[244:245], v86 offset:34944
	ds_read_b64_tr_b16 v[246:247], v86 offset:36032
	ds_read_b64_tr_b16 v[228:229], v86 offset:34976
	ds_read_b64_tr_b16 v[230:231], v86 offset:36064
	ds_read_b64_tr_b16 v[150:151], v86 offset:43648
	ds_read_b64_tr_b16 v[152:153], v86 offset:44736
	ds_read_b64_tr_b16 v[240:241], v86 offset:43680
	ds_read_b64_tr_b16 v[242:243], v86 offset:44768
	s_nop 3
	v_pk_mul_f32 v[66:67], v[58:59], v[66:67]
	v_pk_mul_f32 v[64:65], v[56:57], v[64:65]
	v_pk_fma_f32 v[112:113], v[112:113], v[46:47], v[66:67]
	v_pk_fma_f32 v[106:107], v[106:107], v[44:45], v[64:65]
	v_pk_mul_f32 v[238:239], v[58:59], v[238:239]
	v_pk_mul_f32 v[236:237], v[56:57], v[236:237]
	v_pk_fma_f32 v[118:119], v[118:119], v[46:47], v[238:239]
	v_pk_fma_f32 v[110:111], v[110:111], v[44:45], v[236:237]
	s_waitcnt lgkmcnt(6)
	v_mfma_f32_16x16x32_bf16 v[64:67], v[60:63], v[244:247], 0
	s_waitcnt lgkmcnt(4)
	v_mfma_f32_16x16x32_bf16 v[236:239], v[60:63], v[228:231], 0
	s_waitcnt lgkmcnt(2)
	v_mfma_f32_16x16x32_bf16 v[64:67], v[48:51], v[150:153], v[64:67]
	s_waitcnt lgkmcnt(0)
	v_mfma_f32_16x16x32_bf16 v[236:239], v[48:51], v[240:243], v[236:239]
	ds_read_b64_tr_b16 v[244:245], v86 offset:35008
	ds_read_b64_tr_b16 v[246:247], v86 offset:36096
	ds_read_b64_tr_b16 v[228:229], v86 offset:35040
	ds_read_b64_tr_b16 v[230:231], v86 offset:36128
	ds_read_b64_tr_b16 v[150:151], v86 offset:43712
	ds_read_b64_tr_b16 v[152:153], v86 offset:44800
	ds_read_b64_tr_b16 v[240:241], v86 offset:43744
	ds_read_b64_tr_b16 v[242:243], v86 offset:44832
	s_nop 3
	v_pk_mul_f32 v[66:67], v[58:59], v[66:67]
	v_pk_mul_f32 v[64:65], v[56:57], v[64:65]
	v_pk_fma_f32 v[122:123], v[122:123], v[46:47], v[66:67]
	v_pk_fma_f32 v[116:117], v[116:117], v[44:45], v[64:65]
	v_pk_mul_f32 v[238:239], v[58:59], v[238:239]
	v_pk_mul_f32 v[236:237], v[56:57], v[236:237]
	v_pk_fma_f32 v[126:127], v[126:127], v[46:47], v[238:239]
	v_pk_fma_f32 v[120:121], v[120:121], v[44:45], v[236:237]
	s_waitcnt lgkmcnt(6)
	v_mfma_f32_16x16x32_bf16 v[64:67], v[60:63], v[244:247], 0
	s_waitcnt lgkmcnt(4)
	v_mfma_f32_16x16x32_bf16 v[60:63], v[60:63], v[228:231], 0
	s_waitcnt lgkmcnt(2)
	v_mfma_f32_16x16x32_bf16 v[64:67], v[48:51], v[150:153], v[64:67]
	s_waitcnt lgkmcnt(0)
	s_barrier
	s_waitcnt lgkmcnt(0)
	v_mfma_f32_16x16x32_bf16 v[48:51], v[48:51], v[240:243], v[60:63]
	s_nop 4
	v_pk_mul_f32 v[66:67], v[58:59], v[66:67]
	v_pk_mul_f32 v[64:65], v[56:57], v[64:65]
	v_pk_fma_f32 v[128:129], v[128:129], v[46:47], v[66:67]
	v_pk_fma_f32 v[124:125], v[124:125], v[44:45], v[64:65]
	s_nop 7
	v_pk_mul_f32 v[48:49], v[56:57], v[48:49]
	v_pk_mul_f32 v[50:51], v[58:59], v[50:51]
	v_pk_fma_f32 v[130:131], v[130:131], v[44:45], v[48:49]
	v_mul_f32_e32 v44, v33, v33
	v_mul_f32_e32 v45, v35, v35
	v_fmac_f32_e32 v44, v32, v32
	v_fmac_f32_e32 v45, v34, v34
	v_pk_fma_f32 v[132:133], v[132:133], v[46:47], v[50:51]
	v_add_f32_e32 v44, v44, v45
	v_mul_f32_e32 v45, v37, v37
	v_mul_f32_e32 v46, v39, v39
	v_fmac_f32_e32 v45, v36, v36
	v_fmac_f32_e32 v46, v38, v38
	v_add_f32_e32 v45, v45, v46
	v_add_f32_e32 v44, v44, v45
	v_mul_f32_e32 v45, v53, v53
	v_mul_f32_e32 v46, v55, v55
	v_fmac_f32_e32 v45, v52, v52
	v_fmac_f32_e32 v46, v54, v54
	v_add_f32_e32 v45, v45, v46
	v_add_f32_e32 v44, v44, v45
	v_mul_f32_e32 v45, v41, v41
	v_mul_f32_e32 v46, v43, v43
	v_fmac_f32_e32 v45, v40, v40
	v_fmac_f32_e32 v46, v42, v42
	v_add_f32_e32 v45, v45, v46
	v_and_b32_e32 v46, 64, v210
	v_add_f32_e32 v44, v44, v45
	v_xor_b32_e32 v45, 16, v210
	v_add_u32_e32 v46, 64, v46
	v_cmp_lt_i32_e32 vcc, v45, v46
	s_nop 1
	v_cndmask_b32_e32 v45, v210, v45, vcc
	v_lshlrev_b32_e32 v249, 2, v45
	ds_bpermute_b32 v45, v249, v44
	s_waitcnt lgkmcnt(0)
	v_add_f32_e32 v44, v44, v45
	v_xor_b32_e32 v45, 32, v210
	v_cmp_lt_i32_e32 vcc, v45, v46
	ds_read_b128 v[46:49], v183
	s_waitcnt lgkmcnt(0)
	v_pk_mul_f32 v[50:51], v[104:105], v[48:49]
	v_pk_mul_f32 v[56:57], v[102:103], v[46:47]
	v_cndmask_b32_e32 v45, v210, v45, vcc
	v_cvt_pk_bf16_f32 v56, v56, v57
	v_cvt_pk_bf16_f32 v57, v50, v51
	ds_write_b64 v223, v[56:57]
	v_pk_mul_f32 v[50:51], v[114:115], v[48:49]
	v_pk_mul_f32 v[56:57], v[108:109], v[46:47]
	v_lshlrev_b32_e32 v250, 2, v45
	v_cvt_pk_bf16_f32 v56, v56, v57
	v_cvt_pk_bf16_f32 v57, v50, v51
	ds_write_b64 v223, v[56:57] offset:4352
	v_pk_mul_f32 v[50:51], v[112:113], v[48:49]
	v_pk_mul_f32 v[56:57], v[106:107], v[46:47]
	ds_bpermute_b32 v45, v250, v44
	v_cvt_pk_bf16_f32 v56, v56, v57
	v_cvt_pk_bf16_f32 v57, v50, v51
	ds_write_b64 v223, v[56:57] offset:8704
	v_pk_mul_f32 v[50:51], v[118:119], v[48:49]
	v_pk_mul_f32 v[56:57], v[110:111], v[46:47]
	s_nop 0
	v_cvt_pk_bf16_f32 v56, v56, v57
	v_cvt_pk_bf16_f32 v57, v50, v51
	ds_write_b64 v223, v[56:57] offset:13056
	v_pk_mul_f32 v[50:51], v[122:123], v[48:49]
	v_pk_mul_f32 v[56:57], v[116:117], v[46:47]
	s_nop 0
	v_cvt_pk_bf16_f32 v56, v56, v57
	v_cvt_pk_bf16_f32 v57, v50, v51
	ds_write_b64 v223, v[56:57] offset:17408
	v_pk_mul_f32 v[50:51], v[126:127], v[48:49]
	v_pk_mul_f32 v[56:57], v[120:121], v[46:47]
	s_nop 0
	v_cvt_pk_bf16_f32 v56, v56, v57
	v_cvt_pk_bf16_f32 v57, v50, v51
	ds_write_b64 v223, v[56:57] offset:21760
	v_pk_mul_f32 v[50:51], v[128:129], v[48:49]
	v_pk_mul_f32 v[56:57], v[124:125], v[46:47]
	v_pk_mul_f32 v[48:49], v[132:133], v[48:49]
	v_pk_mul_f32 v[46:47], v[130:131], v[46:47]
	v_cvt_pk_bf16_f32 v56, v56, v57
	v_cvt_pk_bf16_f32 v57, v50, v51
	v_cvt_pk_bf16_f32 v46, v46, v47
	v_cvt_pk_bf16_f32 v47, v48, v49
	ds_write_b64 v223, v[56:57] offset:26112
	ds_write_b64 v223, v[46:47] offset:30464
	s_and_saveexec_b64 s[72:73], s[16:17]
	s_cbranch_execz .LBB0_527
	s_waitcnt lgkmcnt(6)
	v_add_f32_e32 v44, v44, v45
	ds_write_b32 v184, v44

.LBB0_529:
	s_min_u32 s52, s91, 29
	s_lshl_b32 s52, s52, 6
	s_add_i32 s66, s52, 0x80
	s_min_u32 s52, s91, 27
	s_lshl_b32 s52, s52, 6
	s_add_i32 s54, s52, 0x100
	s_add_u32 s52, s62, s54
	s_addc_u32 s53, s63, 0
	v_add_u32_e32 v32, v161, v162
	s_add_u32 s54, s60, s54
	s_waitcnt vmcnt(27)
	ds_write_b128 v32, v[24:27] offset:34816
	v_add_u32_e32 v24, v161, v163
	s_addc_u32 s55, 0, 0
	s_waitcnt vmcnt(26)
	ds_write_b128 v24, v[28:31] offset:34816
	v_lshl_add_u64 v[24:25], v[88:89], 0, s[66:67]
	s_add_u32 s58, s52, s86
	v_lshlrev_b64 v[24:25], 8, v[24:25]
	s_addc_u32 s59, s53, 0
	v_lshl_add_u64 v[24:25], v[90:91], 0, v[24:25]
	s_lshl_b64 s[58:59], s[58:59], 8
	global_load_dwordx2 v[84:85], v[24:25], off
	global_load_dwordx2 v[82:83], v[24:25], off offset:32
	global_load_dwordx2 v[78:79], v[24:25], off offset:64
	global_load_dwordx2 v[76:77], v[24:25], off offset:96
	v_lshl_add_u64 v[24:25], v[70:71], 0, s[58:59]
	s_lshl_b64 s[54:55], s[54:55], 11
	global_load_dword v145, v[24:25], off
	v_lshl_add_u64 v[24:25], v[72:73], 0, s[54:55]
	s_or_b32 s54, s58, 0x100
	s_mov_b32 s55, s59
	v_lshl_add_u64 v[26:27], v[70:71], 0, s[54:55]
	s_or_b32 s54, s58, 0x200
	global_load_dword v144, v[24:25], off
	global_load_dword v146, v[26:27], off
	global_load_dword v143, v[24:25], off offset:2048
	v_lshl_add_u64 v[26:27], v[70:71], 0, s[54:55]
	global_load_dword v138, v[26:27], off
	v_add_co_u32_e32 v26, vcc, s61, v24
	s_or_b32 s54, s58, 0x300
	s_nop 0
	v_addc_co_u32_e32 v27, vcc, 0, v25, vcc
	v_add_co_u32_e32 v28, vcc, s87, v24
	v_lshl_add_u64 v[30:31], v[70:71], 0, s[54:55]
	s_nop 0
	v_addc_co_u32_e32 v29, vcc, 0, v25, vcc
	s_or_b32 s54, s58, 0x400
	global_load_dword v136, v[28:29], off offset:-4096
	global_load_dword v137, v[30:31], off
	global_load_dword v142, v[26:27], off offset:2048
	v_lshl_add_u64 v[26:27], v[70:71], 0, s[54:55]
	s_or_b32 s54, s58, 0x500
	global_load_dword v135, v[26:27], off
	global_load_dword v134, v[28:29], off
	v_lshl_add_u64 v[26:27], v[70:71], 0, s[54:55]
	s_or_b32 s54, s58, 0x600
	v_add_co_u32_e32 v24, vcc, s88, v24
	global_load_dword v139, v[26:27], off
	global_load_dword v141, v[28:29], off offset:2048
	v_lshl_add_u64 v[26:27], v[70:71], 0, s[54:55]
	v_addc_co_u32_e32 v25, vcc, 0, v25, vcc
	s_or_b32 s58, s58, 0x700
	global_load_dword v148, v[26:27], off
	global_load_dword v147, v[24:25], off
	v_lshl_add_u64 v[26:27], v[70:71], 0, s[58:59]
	global_load_dword v140, v[26:27], off
	global_load_dword v155, v[24:25], off offset:2048
	v_mov_b32_e32 v25, s53
	v_or_b32_e32 v24, s52, v93
	v_lshl_add_u64 v[28:29], s[52:53], 0, v[68:69]
	v_lshlrev_b64 v[24:25], 8, v[24:25]
	v_lshlrev_b64 v[28:29], 8, v[28:29]
	v_lshl_add_u64 v[24:25], v[74:75], 0, v[24:25]
	v_lshl_add_u64 v[28:29], v[74:75], 0, v[28:29]
	global_load_dwordx4 v[24:27], v[24:25], off
	s_nop 0
	global_load_dwordx4 v[28:31], v[28:29], off
	ds_read_b128 v[52:55], v218 offset:52224
	ds_read_b128 v[48:51], v218 offset:52288
	ds_read_b128 v[44:47], v218 offset:52352
	ds_read_b128 v[36:39], v218 offset:52416
	ds_read_b128 v[40:43], v211
	ds_read_b128 v[228:231], v211 offset:64
	ds_read_b128 v[232:235], v211 offset:128
	ds_read_b128 v[236:239], v211 offset:192
	s_waitcnt lgkmcnt(3)
	v_mfma_f32_16x16x32_bf16 v[32:35], v[40:43], v[52:55], 0
	s_waitcnt lgkmcnt(2)
	v_mfma_f32_16x16x32_bf16 v[32:35], v[228:231], v[48:51], v[32:35]
	s_waitcnt lgkmcnt(1)
	v_mfma_f32_16x16x32_bf16 v[32:35], v[232:235], v[44:47], v[32:35]
	s_waitcnt lgkmcnt(0)
	v_mfma_f32_16x16x32_bf16 v[32:35], v[236:239], v[36:39], v[32:35]
	ds_read_b128 v[40:43], v211 offset:4352
	ds_read_b128 v[228:231], v211 offset:4416
	ds_read_b128 v[232:235], v211 offset:4480
	ds_read_b128 v[236:239], v211 offset:4544
	s_nop 3
	v_cndmask_b32_e64 v56, 0, v32, s[18:19]
	v_cndmask_b32_e64 v57, 0, v33, s[20:21]
	v_cndmask_b32_e64 v58, 0, v34, s[22:23]
	v_cndmask_b32_e64 v59, 0, v35, s[24:25]
	v_cvt_pk_bf16_f32 v64, v56, v57
	v_cvt_pk_bf16_f32 v65, v58, v59
	s_waitcnt lgkmcnt(3)
	v_mfma_f32_16x16x32_bf16 v[32:35], v[40:43], v[52:55], 0
	s_waitcnt lgkmcnt(2)
	v_mfma_f32_16x16x32_bf16 v[32:35], v[228:231], v[48:51], v[32:35]
	s_waitcnt lgkmcnt(1)
	v_mfma_f32_16x16x32_bf16 v[32:35], v[232:235], v[44:47], v[32:35]
	s_waitcnt lgkmcnt(0)
	v_mfma_f32_16x16x32_bf16 v[32:35], v[236:239], v[36:39], v[32:35]
	ds_read_b128 v[40:43], v211 offset:8704
	ds_read_b128 v[228:231], v211 offset:8768
	ds_read_b128 v[232:235], v211 offset:8832
	ds_read_b128 v[236:239], v211 offset:8896
	s_nop 3
	v_cndmask_b32_e64 v60, 0, v32, s[26:27]
	v_cndmask_b32_e64 v61, 0, v33, s[28:29]
	v_cndmask_b32_e64 v62, 0, v34, s[30:31]
	v_cndmask_b32_e64 v63, 0, v35, s[34:35]
	v_cvt_pk_bf16_f32 v66, v60, v61
	v_cvt_pk_bf16_f32 v67, v62, v63
	s_waitcnt lgkmcnt(3)
	v_mfma_f32_16x16x32_bf16 v[32:35], v[40:43], v[52:55], 0
	s_waitcnt lgkmcnt(2)
	v_mfma_f32_16x16x32_bf16 v[32:35], v[228:231], v[48:51], v[32:35]
	s_waitcnt lgkmcnt(1)
	v_mfma_f32_16x16x32_bf16 v[32:35], v[232:235], v[44:47], v[32:35]
	s_waitcnt lgkmcnt(0)
	v_mfma_f32_16x16x32_bf16 v[32:35], v[236:239], v[36:39], v[32:35]
	ds_read_b128 v[40:43], v211 offset:13056
	ds_read_b128 v[228:231], v211 offset:13120
	ds_read_b128 v[232:235], v211 offset:13184
	ds_read_b128 v[236:239], v211 offset:13248
	s_nop 3
	v_cndmask_b32_e64 v86, 0, v32, s[36:37]
	v_cndmask_b32_e64 v149, 0, v33, s[38:39]
	v_cndmask_b32_e64 v150, 0, v34, s[40:41]
	v_cndmask_b32_e64 v151, 0, v35, s[42:43]
	v_cvt_pk_bf16_f32 v60, v86, v149
	v_cvt_pk_bf16_f32 v61, v150, v151
	v_add_u32_e32 v86, v192, v203
	s_waitcnt lgkmcnt(3)
	v_mfma_f32_16x16x32_bf16 v[32:35], v[40:43], v[52:55], 0
	s_waitcnt lgkmcnt(2)
	v_mfma_f32_16x16x32_bf16 v[32:35], v[228:231], v[48:51], v[32:35]
	s_waitcnt lgkmcnt(1)
	v_mfma_f32_16x16x32_bf16 v[32:35], v[232:235], v[44:47], v[32:35]
	s_waitcnt lgkmcnt(0)
	v_mfma_f32_16x16x32_bf16 v[32:35], v[236:239], v[36:39], v[32:35]
	ds_read_b64_tr_b16 v[150:151], v212 offset:8704
	ds_read_b64_tr_b16 v[152:153], v212 offset:13056
	ds_read_b128 v[228:231], v219
	ds_read_b128 v[232:235], v219 offset:64
	ds_read_b128 v[236:239], v219 offset:128
	ds_read_b128 v[240:243], v219 offset:192
	s_nop 1
	v_cndmask_b32_e64 v32, 0, v32, s[44:45]
	v_cndmask_b32_e64 v33, 0, v33, s[46:47]
	v_cndmask_b32_e64 v34, 0, v34, s[48:49]
	v_cndmask_b32_e64 v35, 0, v35, s[50:51]
	v_cvt_pk_bf16_f32 v62, v32, v33
	v_cvt_pk_bf16_f32 v63, v34, v35
	ds_read_b64_tr_b16 v[32:33], v212
	ds_read_b64_tr_b16 v[34:35], v212 offset:4352
	s_waitcnt lgkmcnt(0)
	v_mfma_f32_16x16x32_bf16 v[32:35], v[32:35], v[64:67], 0
	ds_read_b64_tr_b16 v[40:41], v214
	ds_read_b64_tr_b16 v[42:43], v214 offset:4352
	v_mfma_f32_16x16x32_bf16 v[32:35], v[150:153], v[60:63], v[32:35]
	ds_read_b64_tr_b16 v[150:151], v214 offset:8704
	ds_read_b64_tr_b16 v[152:153], v214 offset:13056
	v_mfma_f32_16x16x32_bf16 v[32:35], v[228:231], v[52:55], v[32:35]
	ds_read_b128 v[228:231], v220
	v_mfma_f32_16x16x32_bf16 v[32:35], v[232:235], v[48:51], v[32:35]
	ds_read_b128 v[232:235], v220 offset:64
	v_mfma_f32_16x16x32_bf16 v[32:35], v[236:239], v[44:47], v[32:35]
	ds_read_b128 v[236:239], v220 offset:128
	v_mfma_f32_16x16x32_bf16 v[32:35], v[240:243], v[36:39], v[32:35]
	ds_read_b128 v[240:243], v220 offset:192
	s_waitcnt lgkmcnt(6)
	v_mfma_f32_16x16x32_bf16 v[40:43], v[40:43], v[64:67], 0
	ds_read_b64_tr_b16 v[56:57], v215
	ds_read_b64_tr_b16 v[58:59], v215 offset:4352
	s_waitcnt lgkmcnt(6)
	v_mfma_f32_16x16x32_bf16 v[40:43], v[150:153], v[60:63], v[40:43]
	ds_read_b64_tr_b16 v[150:151], v215 offset:8704
	ds_read_b64_tr_b16 v[152:153], v215 offset:13056
	s_waitcnt lgkmcnt(7)
	v_mfma_f32_16x16x32_bf16 v[40:43], v[228:231], v[52:55], v[40:43]
	ds_read_b128 v[228:231], v221
	s_waitcnt lgkmcnt(7)
	v_mfma_f32_16x16x32_bf16 v[40:43], v[232:235], v[48:51], v[40:43]
	ds_read_b128 v[232:235], v221 offset:64
	s_waitcnt lgkmcnt(7)
	v_mfma_f32_16x16x32_bf16 v[40:43], v[236:239], v[44:47], v[40:43]
	ds_read_b128 v[236:239], v221 offset:128
	s_waitcnt lgkmcnt(7)
	v_mfma_f32_16x16x32_bf16 v[40:43], v[240:243], v[36:39], v[40:43]
	ds_read_b128 v[240:243], v221 offset:192
	s_waitcnt lgkmcnt(6)
	v_mfma_f32_16x16x32_bf16 v[56:59], v[56:59], v[64:67], 0
	ds_read_b64_tr_b16 v[244:245], v216
	ds_read_b64_tr_b16 v[246:247], v216 offset:4352
	s_waitcnt lgkmcnt(6)
	v_mfma_f32_16x16x32_bf16 v[56:59], v[150:153], v[60:63], v[56:59]
	ds_read_b64_tr_b16 v[150:151], v216 offset:8704
	ds_read_b64_tr_b16 v[152:153], v216 offset:13056
	s_waitcnt lgkmcnt(7)
	v_mfma_f32_16x16x32_bf16 v[56:59], v[228:231], v[52:55], v[56:59]
	ds_read_b128 v[228:231], v222
	s_waitcnt lgkmcnt(7)
	v_mfma_f32_16x16x32_bf16 v[56:59], v[232:235], v[48:51], v[56:59]
	ds_read_b128 v[232:235], v222 offset:64
	s_waitcnt lgkmcnt(7)
	v_mfma_f32_16x16x32_bf16 v[56:59], v[236:239], v[44:47], v[56:59]
	ds_read_b128 v[236:239], v222 offset:128
	s_waitcnt lgkmcnt(7)
	v_mfma_f32_16x16x32_bf16 v[56:59], v[240:243], v[36:39], v[56:59]
	ds_read_b128 v[240:243], v222 offset:192
	s_waitcnt lgkmcnt(6)
	v_mfma_f32_16x16x32_bf16 v[64:67], v[244:247], v[64:67], 0
	s_waitcnt lgkmcnt(4)
	v_mfma_f32_16x16x32_bf16 v[64:67], v[150:153], v[60:63], v[64:67]
	ds_read_b64_tr_b16 v[60:61], v217
	ds_read_b64_tr_b16 v[62:63], v217 offset:1088
	s_waitcnt lgkmcnt(5)
	v_mfma_f32_16x16x32_bf16 v[64:67], v[228:231], v[52:55], v[64:67]
	ds_read_b64_tr_b16 v[52:53], v217 offset:8704
	ds_read_b64_tr_b16 v[54:55], v217 offset:9792
	s_waitcnt lgkmcnt(6)
	v_mfma_f32_16x16x32_bf16 v[64:67], v[232:235], v[48:51], v[64:67]
	ds_read_b128 v[48:51], v195
	s_waitcnt lgkmcnt(6)
	v_mfma_f32_16x16x32_bf16 v[64:67], v[236:239], v[44:47], v[64:67]
	ds_read_b128 v[44:47], v193
	s_waitcnt lgkmcnt(6)
	v_mfma_f32_16x16x32_bf16 v[36:39], v[240:243], v[36:39], v[64:67]
	ds_read_b64_tr_b16 v[244:245], v86
	ds_read_b64_tr_b16 v[246:247], v86 offset:1088
	ds_read_b64_tr_b16 v[230:231], v86 offset:32
	ds_read_b64_tr_b16 v[232:233], v86 offset:1120
	ds_read_b64_tr_b16 v[150:151], v86 offset:8704
	ds_read_b64_tr_b16 v[152:153], v86 offset:9792
	ds_read_b64_tr_b16 v[240:241], v86 offset:8736
	ds_read_b64_tr_b16 v[242:243], v86 offset:9824
	s_waitcnt lgkmcnt(6)
	v_mfma_f32_16x16x32_bf16 v[64:67], v[60:63], v[244:247], 0
	s_waitcnt lgkmcnt(4)
	v_mfma_f32_16x16x32_bf16 v[236:239], v[60:63], v[230:233], 0
	s_waitcnt lgkmcnt(2)
	v_mfma_f32_16x16x32_bf16 v[64:67], v[52:55], v[150:153], v[64:67]
	s_waitcnt lgkmcnt(0)
	v_mfma_f32_16x16x32_bf16 v[236:239], v[52:55], v[240:243], v[236:239]
	ds_read_b64_tr_b16 v[244:245], v86 offset:64
	ds_read_b64_tr_b16 v[246:247], v86 offset:1152
	ds_read_b64_tr_b16 v[230:231], v86 offset:96
	ds_read_b64_tr_b16 v[232:233], v86 offset:1184
	ds_read_b64_tr_b16 v[150:151], v86 offset:8768
	ds_read_b64_tr_b16 v[152:153], v86 offset:9856
	ds_read_b64_tr_b16 v[240:241], v86 offset:8800
	ds_read_b64_tr_b16 v[242:243], v86 offset:9888
	s_nop 3
	v_pk_mul_f32 v[66:67], v[50:51], v[66:67]
	v_pk_mul_f32 v[64:65], v[48:49], v[64:65]
	v_pk_fma_f32 v[104:105], v[104:105], v[46:47], v[66:67]
	v_pk_fma_f32 v[102:103], v[102:103], v[44:45], v[64:65]
	v_pk_mul_f32 v[238:239], v[50:51], v[238:239]
	v_pk_mul_f32 v[236:237], v[48:49], v[236:237]
	v_pk_fma_f32 v[114:115], v[114:115], v[46:47], v[238:239]
	v_pk_fma_f32 v[108:109], v[108:109], v[44:45], v[236:237]
	s_waitcnt lgkmcnt(6)
	v_mfma_f32_16x16x32_bf16 v[64:67], v[60:63], v[244:247], 0
	s_waitcnt lgkmcnt(4)
	v_mfma_f32_16x16x32_bf16 v[236:239], v[60:63], v[230:233], 0
	s_waitcnt lgkmcnt(2)
	v_mfma_f32_16x16x32_bf16 v[64:67], v[52:55], v[150:153], v[64:67]
	s_waitcnt lgkmcnt(0)
	v_mfma_f32_16x16x32_bf16 v[236:239], v[52:55], v[240:243], v[236:239]
	ds_read_b64_tr_b16 v[244:245], v86 offset:128
	ds_read_b64_tr_b16 v[246:247], v86 offset:1216
	ds_read_b64_tr_b16 v[230:231], v86 offset:160
	ds_read_b64_tr_b16 v[232:233], v86 offset:1248
	ds_read_b64_tr_b16 v[150:151], v86 offset:8832
	ds_read_b64_tr_b16 v[152:153], v86 offset:9920
	ds_read_b64_tr_b16 v[240:241], v86 offset:8864
	ds_read_b64_tr_b16 v[242:243], v86 offset:9952
	s_nop 3
	v_pk_mul_f32 v[66:67], v[50:51], v[66:67]
	v_pk_mul_f32 v[64:65], v[48:49], v[64:65]
	v_pk_fma_f32 v[112:113], v[112:113], v[46:47], v[66:67]
	v_pk_fma_f32 v[106:107], v[106:107], v[44:45], v[64:65]
	v_pk_mul_f32 v[238:239], v[50:51], v[238:239]
	v_pk_mul_f32 v[236:237], v[48:49], v[236:237]
	v_pk_fma_f32 v[118:119], v[118:119], v[46:47], v[238:239]
	v_pk_fma_f32 v[110:111], v[110:111], v[44:45], v[236:237]
	s_waitcnt lgkmcnt(6)
	v_mfma_f32_16x16x32_bf16 v[64:67], v[60:63], v[244:247], 0
	s_waitcnt lgkmcnt(4)
	v_mfma_f32_16x16x32_bf16 v[236:239], v[60:63], v[230:233], 0
	s_waitcnt lgkmcnt(2)
	v_mfma_f32_16x16x32_bf16 v[64:67], v[52:55], v[150:153], v[64:67]
	s_waitcnt lgkmcnt(0)
	v_mfma_f32_16x16x32_bf16 v[236:239], v[52:55], v[240:243], v[236:239]
	ds_read_b64_tr_b16 v[244:245], v86 offset:192
	ds_read_b64_tr_b16 v[246:247], v86 offset:1280
	ds_read_b64_tr_b16 v[230:231], v86 offset:224
	ds_read_b64_tr_b16 v[232:233], v86 offset:1312
	ds_read_b64_tr_b16 v[150:151], v86 offset:8896
	ds_read_b64_tr_b16 v[152:153], v86 offset:9984
	ds_read_b64_tr_b16 v[240:241], v86 offset:8928
	ds_read_b64_tr_b16 v[242:243], v86 offset:10016
	s_nop 3
	v_pk_mul_f32 v[66:67], v[50:51], v[66:67]
	v_pk_mul_f32 v[64:65], v[48:49], v[64:65]
	v_pk_fma_f32 v[122:123], v[122:123], v[46:47], v[66:67]
	v_pk_fma_f32 v[116:117], v[116:117], v[44:45], v[64:65]
	v_pk_mul_f32 v[238:239], v[50:51], v[238:239]
	v_pk_mul_f32 v[236:237], v[48:49], v[236:237]
	v_pk_fma_f32 v[126:127], v[126:127], v[46:47], v[238:239]
	v_pk_fma_f32 v[120:121], v[120:121], v[44:45], v[236:237]
	s_waitcnt lgkmcnt(6)
	v_mfma_f32_16x16x32_bf16 v[64:67], v[60:63], v[244:247], 0
	s_waitcnt lgkmcnt(4)
	v_mfma_f32_16x16x32_bf16 v[60:63], v[60:63], v[230:233], 0
	s_waitcnt lgkmcnt(2)
	v_mfma_f32_16x16x32_bf16 v[64:67], v[52:55], v[150:153], v[64:67]
	s_waitcnt lgkmcnt(0)
	s_barrier
	s_waitcnt lgkmcnt(0)
	v_mfma_f32_16x16x32_bf16 v[52:55], v[52:55], v[240:243], v[60:63]
	s_nop 4
	v_pk_mul_f32 v[66:67], v[50:51], v[66:67]
	v_pk_mul_f32 v[64:65], v[48:49], v[64:65]
	v_pk_fma_f32 v[128:129], v[128:129], v[46:47], v[66:67]
	v_pk_fma_f32 v[124:125], v[124:125], v[44:45], v[64:65]
	s_nop 7
	v_pk_mul_f32 v[48:49], v[48:49], v[52:53]
	v_pk_mul_f32 v[50:51], v[50:51], v[54:55]
	v_pk_fma_f32 v[130:131], v[130:131], v[44:45], v[48:49]
	v_mul_f32_e32 v44, v33, v33
	v_mul_f32_e32 v45, v35, v35
	v_fmac_f32_e32 v44, v32, v32
	v_fmac_f32_e32 v45, v34, v34
	v_pk_fma_f32 v[132:133], v[132:133], v[46:47], v[50:51]
	v_add_f32_e32 v44, v44, v45
	v_mul_f32_e32 v45, v41, v41
	v_mul_f32_e32 v46, v43, v43
	v_fmac_f32_e32 v45, v40, v40
	v_fmac_f32_e32 v46, v42, v42
	v_add_f32_e32 v45, v45, v46
	v_add_f32_e32 v44, v44, v45
	v_mul_f32_e32 v45, v57, v57
	v_mul_f32_e32 v46, v59, v59
	v_fmac_f32_e32 v45, v56, v56
	v_fmac_f32_e32 v46, v58, v58
	v_add_f32_e32 v45, v45, v46
	v_add_f32_e32 v44, v44, v45
	v_mul_f32_e32 v45, v37, v37
	v_mul_f32_e32 v46, v39, v39
	v_fmac_f32_e32 v45, v36, v36
	v_fmac_f32_e32 v46, v38, v38
	v_add_f32_e32 v45, v45, v46
	ds_read_b128 v[46:49], v197
	v_add_f32_e32 v44, v44, v45
	ds_bpermute_b32 v45, v249, v44
	s_waitcnt lgkmcnt(1)
	v_pk_mul_f32 v[50:51], v[104:105], v[48:49]
	v_pk_mul_f32 v[52:53], v[102:103], v[46:47]
	s_waitcnt lgkmcnt(0)
	v_add_f32_e32 v44, v44, v45
	v_cvt_pk_bf16_f32 v52, v52, v53
	v_cvt_pk_bf16_f32 v53, v50, v51
	ds_write_b64 v223, v[52:53]
	v_pk_mul_f32 v[50:51], v[114:115], v[48:49]
	v_pk_mul_f32 v[52:53], v[108:109], v[46:47]
	ds_bpermute_b32 v45, v250, v44
	v_cvt_pk_bf16_f32 v52, v52, v53
	v_cvt_pk_bf16_f32 v53, v50, v51
	ds_write_b64 v223, v[52:53] offset:4352
	v_pk_mul_f32 v[50:51], v[112:113], v[48:49]
	v_pk_mul_f32 v[52:53], v[106:107], v[46:47]
	s_nop 0
	v_cvt_pk_bf16_f32 v52, v52, v53
	v_cvt_pk_bf16_f32 v53, v50, v51
	ds_write_b64 v223, v[52:53] offset:8704
	v_pk_mul_f32 v[50:51], v[118:119], v[48:49]
	v_pk_mul_f32 v[52:53], v[110:111], v[46:47]
	s_nop 0
	v_cvt_pk_bf16_f32 v52, v52, v53
	v_cvt_pk_bf16_f32 v53, v50, v51
	ds_write_b64 v223, v[52:53] offset:13056
	v_pk_mul_f32 v[50:51], v[122:123], v[48:49]
	v_pk_mul_f32 v[52:53], v[116:117], v[46:47]
	s_nop 0
	v_cvt_pk_bf16_f32 v52, v52, v53
	v_cvt_pk_bf16_f32 v53, v50, v51
	ds_write_b64 v223, v[52:53] offset:17408
	v_pk_mul_f32 v[50:51], v[126:127], v[48:49]
	v_pk_mul_f32 v[52:53], v[120:121], v[46:47]
	s_nop 0
	v_cvt_pk_bf16_f32 v52, v52, v53
	v_cvt_pk_bf16_f32 v53, v50, v51
	ds_write_b64 v223, v[52:53] offset:21760
	v_pk_mul_f32 v[50:51], v[128:129], v[48:49]
	v_pk_mul_f32 v[52:53], v[124:125], v[46:47]
	v_pk_mul_f32 v[48:49], v[132:133], v[48:49]
	v_pk_mul_f32 v[46:47], v[130:131], v[46:47]
	v_cvt_pk_bf16_f32 v52, v52, v53
	v_cvt_pk_bf16_f32 v53, v50, v51
	v_cvt_pk_bf16_f32 v46, v46, v47
	v_cvt_pk_bf16_f32 v47, v48, v49
	ds_write_b64 v223, v[52:53] offset:26112
	ds_write_b64 v223, v[46:47] offset:30464
	s_and_saveexec_b64 s[52:53], s[16:17]
	s_cbranch_execz .LBB0_500
	s_waitcnt lgkmcnt(7)
	v_add_f32_e32 v44, v44, v45
	ds_write_b32 v184, v44
	s_branch .LBB0_500
